# P9 fused epilogue rewritten by hand: residual loads issued at K-loop exit before the row-sumsq atomics and panel sync, batched bpermutes, counted vmcnt row pipeline
# speedup vs baseline: 1.0036x; 1.0036x over previous
.LBB0_911:
	s_lshl_b32 s0, s6, 8
	s_add_i32 s0, s0, s39
	v_or_b32_e32 v128, s0, v149
	v_lshlrev_b32_e32 v129, 3, v148
	v_lshl_or_b32 v129, s7, 8, v129
	v_or_b32_e32 v129, s26, v129
	v_lshlrev_b32_e32 v242, 12, v128
	v_lshl_add_u32 v242, v129, 2, v242
	v_lshlrev_b32_e32 v243, 2, v128
	v_lshlrev_b32_e32 v129, 2, v129
	v_mov_b32_e32 v255, v148
	s_mov_b32 s8, s90
	s_mov_b32 s9, s91
	s_add_u32 s10, s90, 0x10000
	s_addc_u32 s11, s91, 0
	s_add_u32 s12, s90, 0x20000
	s_addc_u32 s13, s91, 0
	s_add_u32 s14, s90, 0x30000
	s_addc_u32 s15, s91, 0
	s_add_u32 s16, s90, 0x80000
	s_addc_u32 s17, s91, 0
	s_add_u32 s18, s90, 0x90000
	s_addc_u32 s19, s91, 0
	s_add_u32 s20, s90, 0xa0000
	s_addc_u32 s21, s91, 0
	s_add_u32 s22, s90, 0xb0000
	s_addc_u32 s23, s91, 0
	global_load_dwordx4 v[130:133], v242, s[8:9]
	global_load_dwordx4 v[134:137], v242, s[8:9] offset:16
	global_load_dwordx4 v[138:141], v242, s[8:9] offset:512
	global_load_dwordx4 v[142:145], v242, s[8:9] offset:528
	global_load_dwordx4 v[146:149], v242, s[10:11]
	global_load_dwordx4 v[150:153], v242, s[10:11] offset:16
	global_load_dwordx4 v[154:157], v242, s[10:11] offset:512
	global_load_dwordx4 v[158:161], v242, s[10:11] offset:528
	global_load_dwordx4 v[162:165], v242, s[12:13]
	global_load_dwordx4 v[166:169], v242, s[12:13] offset:16
	global_load_dwordx4 v[170:173], v242, s[12:13] offset:512
	global_load_dwordx4 v[174:177], v242, s[12:13] offset:528
	global_load_dwordx4 v[178:181], v242, s[14:15]
	global_load_dwordx4 v[182:185], v242, s[14:15] offset:16
	global_load_dwordx4 v[186:189], v242, s[14:15] offset:512
	global_load_dwordx4 v[190:193], v242, s[14:15] offset:528
	s_cmpk_gt_u32 s27, 0xff
	s_cbranch_scc1 .LBB0_913
	s_barrier
.LBB0_913:
	v_mbcnt_lo_u32_b32 v244, -1, 0
	v_mbcnt_hi_u32_b32 v244, -1, v244
	v_xor_b32_e32 v245, 32, v244
	v_xor_b32_e32 v244, 16, v244
	v_lshlrev_b32_e32 v245, 2, v245
	v_lshlrev_b32_e32 v244, 2, v244
	v_mul_f32_e32 v194, v124, v124
	v_mul_f32_e32 v195, v120, v120
	v_mul_f32_e32 v196, v112, v112
	v_mul_f32_e32 v197, v104, v104
	v_fmac_f32_e32 v194, v125, v125
	v_fmac_f32_e32 v195, v121, v121
	v_fmac_f32_e32 v196, v113, v113
	v_fmac_f32_e32 v197, v105, v105
	v_fmac_f32_e32 v194, v126, v126
	v_fmac_f32_e32 v195, v122, v122
	v_fmac_f32_e32 v196, v114, v114
	v_fmac_f32_e32 v197, v106, v106
	v_fmac_f32_e32 v194, v127, v127
	v_fmac_f32_e32 v195, v123, v123
	v_fmac_f32_e32 v196, v115, v115
	v_fmac_f32_e32 v197, v107, v107
	v_add_f32_e32 v194, v194, v195
	v_add_f32_e32 v196, v196, v197
	v_add_f32_e32 v247, v194, v196
	v_mul_f32_e32 v198, v116, v116
	v_mul_f32_e32 v199, v108, v108
	v_mul_f32_e32 v200, v100, v100
	v_mul_f32_e32 v201, v96, v96
	v_fmac_f32_e32 v198, v117, v117
	v_fmac_f32_e32 v199, v109, v109
	v_fmac_f32_e32 v200, v101, v101
	v_fmac_f32_e32 v201, v97, v97
	v_fmac_f32_e32 v198, v118, v118
	v_fmac_f32_e32 v199, v110, v110
	v_fmac_f32_e32 v200, v102, v102
	v_fmac_f32_e32 v201, v98, v98
	v_fmac_f32_e32 v198, v119, v119
	v_fmac_f32_e32 v199, v111, v111
	v_fmac_f32_e32 v200, v103, v103
	v_fmac_f32_e32 v201, v99, v99
	v_add_f32_e32 v198, v198, v199
	v_add_f32_e32 v200, v200, v201
	v_add_f32_e32 v248, v198, v200
	v_mul_f32_e32 v202, v92, v92
	v_mul_f32_e32 v203, v88, v88
	v_mul_f32_e32 v204, v80, v80
	v_mul_f32_e32 v205, v72, v72
	v_fmac_f32_e32 v202, v93, v93
	v_fmac_f32_e32 v203, v89, v89
	v_fmac_f32_e32 v204, v81, v81
	v_fmac_f32_e32 v205, v73, v73
	v_fmac_f32_e32 v202, v94, v94
	v_fmac_f32_e32 v203, v90, v90
	v_fmac_f32_e32 v204, v82, v82
	v_fmac_f32_e32 v205, v74, v74
	v_fmac_f32_e32 v202, v95, v95
	v_fmac_f32_e32 v203, v91, v91
	v_fmac_f32_e32 v204, v83, v83
	v_fmac_f32_e32 v205, v75, v75
	v_add_f32_e32 v202, v202, v203
	v_add_f32_e32 v204, v204, v205
	v_add_f32_e32 v249, v202, v204
	v_mul_f32_e32 v206, v84, v84
	v_mul_f32_e32 v207, v76, v76
	v_mul_f32_e32 v208, v68, v68
	v_mul_f32_e32 v209, v64, v64
	v_fmac_f32_e32 v206, v85, v85
	v_fmac_f32_e32 v207, v77, v77
	v_fmac_f32_e32 v208, v69, v69
	v_fmac_f32_e32 v209, v65, v65
	v_fmac_f32_e32 v206, v86, v86
	v_fmac_f32_e32 v207, v78, v78
	v_fmac_f32_e32 v208, v70, v70
	v_fmac_f32_e32 v209, v66, v66
	v_fmac_f32_e32 v206, v87, v87
	v_fmac_f32_e32 v207, v79, v79
	v_fmac_f32_e32 v208, v71, v71
	v_fmac_f32_e32 v209, v67, v67
	v_add_f32_e32 v206, v206, v207
	v_add_f32_e32 v208, v208, v209
	v_add_f32_e32 v250, v206, v208
	v_mul_f32_e32 v210, v60, v60
	v_mul_f32_e32 v211, v56, v56
	v_mul_f32_e32 v212, v44, v44
	v_mul_f32_e32 v213, v40, v40
	v_fmac_f32_e32 v210, v61, v61
	v_fmac_f32_e32 v211, v57, v57
	v_fmac_f32_e32 v212, v45, v45
	v_fmac_f32_e32 v213, v41, v41
	v_fmac_f32_e32 v210, v62, v62
	v_fmac_f32_e32 v211, v58, v58
	v_fmac_f32_e32 v212, v46, v46
	v_fmac_f32_e32 v213, v42, v42
	v_fmac_f32_e32 v210, v63, v63
	v_fmac_f32_e32 v211, v59, v59
	v_fmac_f32_e32 v212, v47, v47
	v_fmac_f32_e32 v213, v43, v43
	v_add_f32_e32 v210, v210, v211
	v_add_f32_e32 v212, v212, v213
	v_add_f32_e32 v251, v210, v212
	v_mul_f32_e32 v214, v52, v52
	v_mul_f32_e32 v215, v48, v48
	v_mul_f32_e32 v216, v36, v36
	v_mul_f32_e32 v217, v32, v32
	v_fmac_f32_e32 v214, v53, v53
	v_fmac_f32_e32 v215, v49, v49
	v_fmac_f32_e32 v216, v37, v37
	v_fmac_f32_e32 v217, v33, v33
	v_fmac_f32_e32 v214, v54, v54
	v_fmac_f32_e32 v215, v50, v50
	v_fmac_f32_e32 v216, v38, v38
	v_fmac_f32_e32 v217, v34, v34
	v_fmac_f32_e32 v214, v55, v55
	v_fmac_f32_e32 v215, v51, v51
	v_fmac_f32_e32 v216, v39, v39
	v_fmac_f32_e32 v217, v35, v35
	v_add_f32_e32 v214, v214, v215
	v_add_f32_e32 v216, v216, v217
	v_add_f32_e32 v252, v214, v216
	v_mul_f32_e32 v218, v28, v28
	v_mul_f32_e32 v219, v24, v24
	v_mul_f32_e32 v220, v12, v12
	v_mul_f32_e32 v221, v8, v8
	v_fmac_f32_e32 v218, v29, v29
	v_fmac_f32_e32 v219, v25, v25
	v_fmac_f32_e32 v220, v13, v13
	v_fmac_f32_e32 v221, v9, v9
	v_fmac_f32_e32 v218, v30, v30
	v_fmac_f32_e32 v219, v26, v26
	v_fmac_f32_e32 v220, v14, v14
	v_fmac_f32_e32 v221, v10, v10
	v_fmac_f32_e32 v218, v31, v31
	v_fmac_f32_e32 v219, v27, v27
	v_fmac_f32_e32 v220, v15, v15
	v_fmac_f32_e32 v221, v11, v11
	v_add_f32_e32 v218, v218, v219
	v_add_f32_e32 v220, v220, v221
	v_add_f32_e32 v253, v218, v220
	v_mul_f32_e32 v222, v20, v20
	v_mul_f32_e32 v223, v16, v16
	v_mul_f32_e32 v224, v4, v4
	v_mul_f32_e32 v225, v0, v0
	v_fmac_f32_e32 v222, v21, v21
	v_fmac_f32_e32 v223, v17, v17
	v_fmac_f32_e32 v224, v5, v5
	v_fmac_f32_e32 v225, v1, v1
	v_fmac_f32_e32 v222, v22, v22
	v_fmac_f32_e32 v223, v18, v18
	v_fmac_f32_e32 v224, v6, v6
	v_fmac_f32_e32 v225, v2, v2
	v_fmac_f32_e32 v222, v23, v23
	v_fmac_f32_e32 v223, v19, v19
	v_fmac_f32_e32 v224, v7, v7
	v_fmac_f32_e32 v225, v3, v3
	v_add_f32_e32 v222, v222, v223
	v_add_f32_e32 v224, v224, v225
	v_add_f32_e32 v254, v222, v224
	ds_bpermute_b32 v194, v244, v247
	ds_bpermute_b32 v195, v244, v248
	ds_bpermute_b32 v196, v244, v249
	ds_bpermute_b32 v197, v244, v250
	ds_bpermute_b32 v198, v244, v251
	ds_bpermute_b32 v199, v244, v252
	ds_bpermute_b32 v200, v244, v253
	ds_bpermute_b32 v201, v244, v254
	s_waitcnt lgkmcnt(0)
	v_add_f32_e32 v247, v247, v194
	v_add_f32_e32 v248, v248, v195
	v_add_f32_e32 v249, v249, v196
	v_add_f32_e32 v250, v250, v197
	v_add_f32_e32 v251, v251, v198
	v_add_f32_e32 v252, v252, v199
	v_add_f32_e32 v253, v253, v200
	v_add_f32_e32 v254, v254, v201
	ds_bpermute_b32 v194, v245, v247
	ds_bpermute_b32 v195, v245, v248
	ds_bpermute_b32 v196, v245, v249
	ds_bpermute_b32 v197, v245, v250
	ds_bpermute_b32 v198, v245, v251
	ds_bpermute_b32 v199, v245, v252
	ds_bpermute_b32 v200, v245, v253
	ds_bpermute_b32 v201, v245, v254
	s_waitcnt lgkmcnt(0)
	v_add_f32_e32 v247, v247, v194
	v_add_f32_e32 v248, v248, v195
	v_add_f32_e32 v249, v249, v196
	v_add_f32_e32 v250, v250, v197
	v_add_f32_e32 v251, v251, v198
	v_add_f32_e32 v252, v252, v199
	v_add_f32_e32 v253, v253, v200
	v_add_f32_e32 v254, v254, v201
	s_cmp_lt_i32 s6, 48
	s_movk_i32 s0, 0x1800
	s_cselect_b32 s0, s0, 0x3000
	s_cmp_gt_i32 s6, 31
	s_cselect_b32 s0, s0, 0
	s_lshl_b32 s0, s0, 2
	s_add_u32 s28, s92, s0
	s_addc_u32 s29, s93, 0
	s_add_u32 s28, s28, 0x45000
	s_addc_u32 s29, s29, 0
	s_add_u32 s30, s80, 0x5000
	s_addc_u32 s31, s81, 0
	s_add_u32 s24, s92, 0x30000
	s_addc_u32 s25, s93, 0
	global_load_dwordx4 v[226:229], v129, s[28:29]
	global_load_dwordx4 v[194:197], v129, s[30:31]
	global_load_dwordx4 v[210:213], v129, s[56:57]
	global_load_dwordx4 v[230:233], v129, s[28:29] offset:16
	global_load_dwordx4 v[198:201], v129, s[30:31] offset:16
	global_load_dwordx4 v[214:217], v129, s[56:57] offset:16
	global_load_dwordx4 v[234:237], v129, s[28:29] offset:512
	global_load_dwordx4 v[202:205], v129, s[30:31] offset:512
	global_load_dwordx4 v[218:221], v129, s[56:57] offset:512
	global_load_dwordx4 v[238:241], v129, s[28:29] offset:528
	global_load_dwordx4 v[206:209], v129, s[30:31] offset:528
	global_load_dwordx4 v[222:225], v129, s[56:57] offset:528
	v_cmp_eq_u32_e32 vcc, 0, v255
	s_nop 1
	s_and_saveexec_b64 s[0:1], vcc
	global_atomic_add_f32 v243, v247, s[24:25]
	global_atomic_add_f32 v243, v248, s[24:25] offset:64
	global_atomic_add_f32 v243, v249, s[24:25] offset:128
	global_atomic_add_f32 v243, v250, s[24:25] offset:192
	global_atomic_add_f32 v243, v251, s[24:25] offset:512
	global_atomic_add_f32 v243, v252, s[24:25] offset:576
	global_atomic_add_f32 v243, v253, s[24:25] offset:640
	global_atomic_add_f32 v243, v254, s[24:25] offset:704
	s_or_b64 exec, exec, s[0:1]
	s_waitcnt vmcnt(0) lgkmcnt(0)
	s_barrier
	s_mov_b64 s[0:1], exec
	v_readlane_b32 s2, v246, 2
	v_readlane_b32 s3, v246, 3
	s_and_b64 s[2:3], s[0:1], s[2:3]
	s_mov_b64 exec, s[2:3]
	s_cbranch_execz .Lp9_sync_done
	s_lshl_b32 s2, s6, 8
	s_add_u32 s2, s92, s2
	s_addc_u32 s3, s93, 0
	s_add_u32 s2, s2, 0xc000
	s_addc_u32 s3, s3, 0
	v_mov_b32_e32 v128, 0
	v_mov_b32_e32 v129, 1
	global_atomic_add v128, v129, s[2:3]
	s_mov_b32 s4, 0x400000
.Lp9_poll:
	global_load_dword v129, v128, s[2:3] sc1
	s_waitcnt vmcnt(0)
	v_cmp_lt_u32_e32 vcc, 3, v129
	s_cbranch_vccnz .Lp9_sync_done
	s_sleep 1
	s_sub_u32 s4, s4, 1
	s_cmp_lg_u32 s4, 0
	s_cbranch_scc1 .Lp9_poll
.Lp9_sync_done:
	s_mov_b64 exec, s[0:1]
	s_barrier
	global_load_dword v247, v243, s[24:25] sc1
	global_load_dword v248, v243, s[24:25] offset:64 sc1
	global_load_dword v249, v243, s[24:25] offset:128 sc1
	global_load_dword v250, v243, s[24:25] offset:192 sc1
	global_load_dword v251, v243, s[24:25] offset:512 sc1
	global_load_dword v252, v243, s[24:25] offset:576 sc1
	global_load_dword v253, v243, s[24:25] offset:640 sc1
	global_load_dword v254, v243, s[24:25] offset:704 sc1
	v_pk_add_f32 v[226:227], v[226:227], v[194:195]
	v_pk_add_f32 v[228:229], v[228:229], v[196:197]
	v_pk_add_f32 v[230:231], v[230:231], v[198:199]
	v_pk_add_f32 v[232:233], v[232:233], v[200:201]
	v_pk_add_f32 v[234:235], v[234:235], v[202:203]
	v_pk_add_f32 v[236:237], v[236:237], v[204:205]
	v_pk_add_f32 v[238:239], v[238:239], v[206:207]
	v_pk_add_f32 v[240:241], v[240:241], v[208:209]
	v_pk_mul_f32 v[226:227], v[226:227], v[210:211]
	v_pk_mul_f32 v[228:229], v[228:229], v[212:213]
	v_pk_mul_f32 v[230:231], v[230:231], v[214:215]
	v_pk_mul_f32 v[232:233], v[232:233], v[216:217]
	v_pk_mul_f32 v[234:235], v[234:235], v[218:219]
	v_pk_mul_f32 v[236:237], v[236:237], v[220:221]
	v_pk_mul_f32 v[238:239], v[238:239], v[222:223]
	v_pk_mul_f32 v[240:241], v[240:241], v[224:225]
	global_load_dwordx4 v[194:197], v242, s[16:17]
	global_load_dwordx4 v[198:201], v242, s[16:17] offset:16
	global_load_dwordx4 v[202:205], v242, s[16:17] offset:512
	global_load_dwordx4 v[206:209], v242, s[16:17] offset:528
	global_load_dwordx4 v[210:213], v242, s[18:19]
	global_load_dwordx4 v[214:217], v242, s[18:19] offset:16
	global_load_dwordx4 v[218:221], v242, s[18:19] offset:512
	global_load_dwordx4 v[222:225], v242, s[18:19] offset:528
	v_mov_b32_e32 v129, 0x358637bd
	s_mov_b32 s2, 0x3a800000
	s_waitcnt vmcnt(8)
	v_fma_f32 v247, v247, s2, v129
	v_fma_f32 v248, v248, s2, v129
	v_fma_f32 v249, v249, s2, v129
	v_fma_f32 v250, v250, s2, v129
	v_fma_f32 v251, v251, s2, v129
	v_fma_f32 v252, v252, s2, v129
	v_fma_f32 v253, v253, s2, v129
	v_fma_f32 v254, v254, s2, v129
	v_rsq_f32_e32 v247, v247
	v_rsq_f32_e32 v248, v248
	v_rsq_f32_e32 v249, v249
	v_rsq_f32_e32 v250, v250
	v_rsq_f32_e32 v251, v251
	v_rsq_f32_e32 v252, v252
	v_rsq_f32_e32 v253, v253
	v_rsq_f32_e32 v254, v254
	s_nop 0
	v_mov_b32_e32 v128, v247
	v_pk_mul_f32 v[124:125], v[124:125], v[128:129] op_sel_hi:[1,0]
	v_pk_mul_f32 v[126:127], v[126:127], v[128:129] op_sel_hi:[1,0]
	v_pk_mul_f32 v[120:121], v[120:121], v[128:129] op_sel_hi:[1,0]
	v_pk_mul_f32 v[122:123], v[122:123], v[128:129] op_sel_hi:[1,0]
	v_pk_mul_f32 v[112:113], v[112:113], v[128:129] op_sel_hi:[1,0]
	v_pk_mul_f32 v[114:115], v[114:115], v[128:129] op_sel_hi:[1,0]
	v_pk_mul_f32 v[104:105], v[104:105], v[128:129] op_sel_hi:[1,0]
	v_pk_mul_f32 v[106:107], v[106:107], v[128:129] op_sel_hi:[1,0]
	v_pk_fma_f32 v[130:131], v[226:227], v[124:125], v[130:131]
	v_pk_fma_f32 v[132:133], v[228:229], v[126:127], v[132:133]
	v_pk_fma_f32 v[134:135], v[230:231], v[120:121], v[134:135]
	v_pk_fma_f32 v[136:137], v[232:233], v[122:123], v[136:137]
	v_pk_fma_f32 v[138:139], v[234:235], v[112:113], v[138:139]
	v_pk_fma_f32 v[140:141], v[236:237], v[114:115], v[140:141]
	v_pk_fma_f32 v[142:143], v[238:239], v[104:105], v[142:143]
	v_pk_fma_f32 v[144:145], v[240:241], v[106:107], v[144:145]
	global_store_dwordx4 v242, v[130:133], s[8:9]
	global_store_dwordx4 v242, v[134:137], s[8:9] offset:16
	global_store_dwordx4 v242, v[138:141], s[8:9] offset:512
	global_store_dwordx4 v242, v[142:145], s[8:9] offset:528
	v_mov_b32_e32 v128, v248
	v_pk_mul_f32 v[116:117], v[116:117], v[128:129] op_sel_hi:[1,0]
	v_pk_mul_f32 v[118:119], v[118:119], v[128:129] op_sel_hi:[1,0]
	v_pk_mul_f32 v[108:109], v[108:109], v[128:129] op_sel_hi:[1,0]
	v_pk_mul_f32 v[110:111], v[110:111], v[128:129] op_sel_hi:[1,0]
	v_pk_mul_f32 v[100:101], v[100:101], v[128:129] op_sel_hi:[1,0]
	v_pk_mul_f32 v[102:103], v[102:103], v[128:129] op_sel_hi:[1,0]
	v_pk_mul_f32 v[96:97], v[96:97], v[128:129] op_sel_hi:[1,0]
	v_pk_mul_f32 v[98:99], v[98:99], v[128:129] op_sel_hi:[1,0]
	v_pk_fma_f32 v[146:147], v[226:227], v[116:117], v[146:147]
	v_pk_fma_f32 v[148:149], v[228:229], v[118:119], v[148:149]
	v_pk_fma_f32 v[150:151], v[230:231], v[108:109], v[150:151]
	v_pk_fma_f32 v[152:153], v[232:233], v[110:111], v[152:153]
	v_pk_fma_f32 v[154:155], v[234:235], v[100:101], v[154:155]
	v_pk_fma_f32 v[156:157], v[236:237], v[102:103], v[156:157]
	v_pk_fma_f32 v[158:159], v[238:239], v[96:97], v[158:159]
	v_pk_fma_f32 v[160:161], v[240:241], v[98:99], v[160:161]
	global_store_dwordx4 v242, v[146:149], s[10:11]
	global_store_dwordx4 v242, v[150:153], s[10:11] offset:16
	global_store_dwordx4 v242, v[154:157], s[10:11] offset:512
	global_store_dwordx4 v242, v[158:161], s[10:11] offset:528
	global_load_dwordx4 v[130:133], v242, s[20:21]
	global_load_dwordx4 v[134:137], v242, s[20:21] offset:16
	global_load_dwordx4 v[138:141], v242, s[20:21] offset:512
	global_load_dwordx4 v[142:145], v242, s[20:21] offset:528
	v_mov_b32_e32 v128, v249
	v_pk_mul_f32 v[92:93], v[92:93], v[128:129] op_sel_hi:[1,0]
	v_pk_mul_f32 v[94:95], v[94:95], v[128:129] op_sel_hi:[1,0]
	v_pk_mul_f32 v[88:89], v[88:89], v[128:129] op_sel_hi:[1,0]
	v_pk_mul_f32 v[90:91], v[90:91], v[128:129] op_sel_hi:[1,0]
	v_pk_mul_f32 v[80:81], v[80:81], v[128:129] op_sel_hi:[1,0]
	v_pk_mul_f32 v[82:83], v[82:83], v[128:129] op_sel_hi:[1,0]
	v_pk_mul_f32 v[72:73], v[72:73], v[128:129] op_sel_hi:[1,0]
	v_pk_mul_f32 v[74:75], v[74:75], v[128:129] op_sel_hi:[1,0]
	v_pk_fma_f32 v[162:163], v[226:227], v[92:93], v[162:163]
	v_pk_fma_f32 v[164:165], v[228:229], v[94:95], v[164:165]
	v_pk_fma_f32 v[166:167], v[230:231], v[88:89], v[166:167]
	v_pk_fma_f32 v[168:169], v[232:233], v[90:91], v[168:169]
	v_pk_fma_f32 v[170:171], v[234:235], v[80:81], v[170:171]
	v_pk_fma_f32 v[172:173], v[236:237], v[82:83], v[172:173]
	v_pk_fma_f32 v[174:175], v[238:239], v[72:73], v[174:175]
	v_pk_fma_f32 v[176:177], v[240:241], v[74:75], v[176:177]
	global_store_dwordx4 v242, v[162:165], s[12:13]
	global_store_dwordx4 v242, v[166:169], s[12:13] offset:16
	global_store_dwordx4 v242, v[170:173], s[12:13] offset:512
	global_store_dwordx4 v242, v[174:177], s[12:13] offset:528
	global_load_dwordx4 v[146:149], v242, s[22:23]
	global_load_dwordx4 v[150:153], v242, s[22:23] offset:16
	global_load_dwordx4 v[154:157], v242, s[22:23] offset:512
	global_load_dwordx4 v[158:161], v242, s[22:23] offset:528
	v_mov_b32_e32 v128, v250
	v_pk_mul_f32 v[84:85], v[84:85], v[128:129] op_sel_hi:[1,0]
	v_pk_mul_f32 v[86:87], v[86:87], v[128:129] op_sel_hi:[1,0]
	v_pk_mul_f32 v[76:77], v[76:77], v[128:129] op_sel_hi:[1,0]
	v_pk_mul_f32 v[78:79], v[78:79], v[128:129] op_sel_hi:[1,0]
	v_pk_mul_f32 v[68:69], v[68:69], v[128:129] op_sel_hi:[1,0]
	v_pk_mul_f32 v[70:71], v[70:71], v[128:129] op_sel_hi:[1,0]
	v_pk_mul_f32 v[64:65], v[64:65], v[128:129] op_sel_hi:[1,0]
	v_pk_mul_f32 v[66:67], v[66:67], v[128:129] op_sel_hi:[1,0]
	v_pk_fma_f32 v[178:179], v[226:227], v[84:85], v[178:179]
	v_pk_fma_f32 v[180:181], v[228:229], v[86:87], v[180:181]
	v_pk_fma_f32 v[182:183], v[230:231], v[76:77], v[182:183]
	v_pk_fma_f32 v[184:185], v[232:233], v[78:79], v[184:185]
	v_pk_fma_f32 v[186:187], v[234:235], v[68:69], v[186:187]
	v_pk_fma_f32 v[188:189], v[236:237], v[70:71], v[188:189]
	v_pk_fma_f32 v[190:191], v[238:239], v[64:65], v[190:191]
	v_pk_fma_f32 v[192:193], v[240:241], v[66:67], v[192:193]
	global_store_dwordx4 v242, v[178:181], s[14:15]
	global_store_dwordx4 v242, v[182:185], s[14:15] offset:16
	global_store_dwordx4 v242, v[186:189], s[14:15] offset:512
	global_store_dwordx4 v242, v[190:193], s[14:15] offset:528
	s_waitcnt vmcnt(28)
	v_mov_b32_e32 v128, v251
	v_pk_mul_f32 v[60:61], v[60:61], v[128:129] op_sel_hi:[1,0]
	v_pk_mul_f32 v[62:63], v[62:63], v[128:129] op_sel_hi:[1,0]
	v_pk_mul_f32 v[56:57], v[56:57], v[128:129] op_sel_hi:[1,0]
	v_pk_mul_f32 v[58:59], v[58:59], v[128:129] op_sel_hi:[1,0]
	v_pk_mul_f32 v[44:45], v[44:45], v[128:129] op_sel_hi:[1,0]
	v_pk_mul_f32 v[46:47], v[46:47], v[128:129] op_sel_hi:[1,0]
	v_pk_mul_f32 v[40:41], v[40:41], v[128:129] op_sel_hi:[1,0]
	v_pk_mul_f32 v[42:43], v[42:43], v[128:129] op_sel_hi:[1,0]
	v_pk_fma_f32 v[194:195], v[226:227], v[60:61], v[194:195]
	v_pk_fma_f32 v[196:197], v[228:229], v[62:63], v[196:197]
	v_pk_fma_f32 v[198:199], v[230:231], v[56:57], v[198:199]
	v_pk_fma_f32 v[200:201], v[232:233], v[58:59], v[200:201]
	v_pk_fma_f32 v[202:203], v[234:235], v[44:45], v[202:203]
	v_pk_fma_f32 v[204:205], v[236:237], v[46:47], v[204:205]
	v_pk_fma_f32 v[206:207], v[238:239], v[40:41], v[206:207]
	v_pk_fma_f32 v[208:209], v[240:241], v[42:43], v[208:209]
	global_store_dwordx4 v242, v[194:197], s[16:17]
	global_store_dwordx4 v242, v[198:201], s[16:17] offset:16
	global_store_dwordx4 v242, v[202:205], s[16:17] offset:512
	global_store_dwordx4 v242, v[206:209], s[16:17] offset:528
	s_waitcnt vmcnt(28)
	v_mov_b32_e32 v128, v252
	v_pk_mul_f32 v[52:53], v[52:53], v[128:129] op_sel_hi:[1,0]
	v_pk_mul_f32 v[54:55], v[54:55], v[128:129] op_sel_hi:[1,0]
	v_pk_mul_f32 v[48:49], v[48:49], v[128:129] op_sel_hi:[1,0]
	v_pk_mul_f32 v[50:51], v[50:51], v[128:129] op_sel_hi:[1,0]
	v_pk_mul_f32 v[36:37], v[36:37], v[128:129] op_sel_hi:[1,0]
	v_pk_mul_f32 v[38:39], v[38:39], v[128:129] op_sel_hi:[1,0]
	v_pk_mul_f32 v[32:33], v[32:33], v[128:129] op_sel_hi:[1,0]
	v_pk_mul_f32 v[34:35], v[34:35], v[128:129] op_sel_hi:[1,0]
	v_pk_fma_f32 v[210:211], v[226:227], v[52:53], v[210:211]
	v_pk_fma_f32 v[212:213], v[228:229], v[54:55], v[212:213]
	v_pk_fma_f32 v[214:215], v[230:231], v[48:49], v[214:215]
	v_pk_fma_f32 v[216:217], v[232:233], v[50:51], v[216:217]
	v_pk_fma_f32 v[218:219], v[234:235], v[36:37], v[218:219]
	v_pk_fma_f32 v[220:221], v[236:237], v[38:39], v[220:221]
	v_pk_fma_f32 v[222:223], v[238:239], v[32:33], v[222:223]
	v_pk_fma_f32 v[224:225], v[240:241], v[34:35], v[224:225]
	global_store_dwordx4 v242, v[210:213], s[18:19]
	global_store_dwordx4 v242, v[214:217], s[18:19] offset:16
	global_store_dwordx4 v242, v[218:221], s[18:19] offset:512
	global_store_dwordx4 v242, v[222:225], s[18:19] offset:528
	s_waitcnt vmcnt(20)
	v_mov_b32_e32 v128, v253
	v_pk_mul_f32 v[28:29], v[28:29], v[128:129] op_sel_hi:[1,0]
	v_pk_mul_f32 v[30:31], v[30:31], v[128:129] op_sel_hi:[1,0]
	v_pk_mul_f32 v[24:25], v[24:25], v[128:129] op_sel_hi:[1,0]
	v_pk_mul_f32 v[26:27], v[26:27], v[128:129] op_sel_hi:[1,0]
	v_pk_mul_f32 v[12:13], v[12:13], v[128:129] op_sel_hi:[1,0]
	v_pk_mul_f32 v[14:15], v[14:15], v[128:129] op_sel_hi:[1,0]
	v_pk_mul_f32 v[8:9], v[8:9], v[128:129] op_sel_hi:[1,0]
	v_pk_mul_f32 v[10:11], v[10:11], v[128:129] op_sel_hi:[1,0]
	v_pk_fma_f32 v[130:131], v[226:227], v[28:29], v[130:131]
	v_pk_fma_f32 v[132:133], v[228:229], v[30:31], v[132:133]
	v_pk_fma_f32 v[134:135], v[230:231], v[24:25], v[134:135]
	v_pk_fma_f32 v[136:137], v[232:233], v[26:27], v[136:137]
	v_pk_fma_f32 v[138:139], v[234:235], v[12:13], v[138:139]
	v_pk_fma_f32 v[140:141], v[236:237], v[14:15], v[140:141]
	v_pk_fma_f32 v[142:143], v[238:239], v[8:9], v[142:143]
	v_pk_fma_f32 v[144:145], v[240:241], v[10:11], v[144:145]
	global_store_dwordx4 v242, v[130:133], s[20:21]
	global_store_dwordx4 v242, v[134:137], s[20:21] offset:16
	global_store_dwordx4 v242, v[138:141], s[20:21] offset:512
	global_store_dwordx4 v242, v[142:145], s[20:21] offset:528
	s_waitcnt vmcnt(16)
	v_mov_b32_e32 v128, v254
	v_pk_mul_f32 v[20:21], v[20:21], v[128:129] op_sel_hi:[1,0]
	v_pk_mul_f32 v[22:23], v[22:23], v[128:129] op_sel_hi:[1,0]
	v_pk_mul_f32 v[16:17], v[16:17], v[128:129] op_sel_hi:[1,0]
	v_pk_mul_f32 v[18:19], v[18:19], v[128:129] op_sel_hi:[1,0]
	v_pk_mul_f32 v[4:5], v[4:5], v[128:129] op_sel_hi:[1,0]
	v_pk_mul_f32 v[6:7], v[6:7], v[128:129] op_sel_hi:[1,0]
	v_pk_mul_f32 v[0:1], v[0:1], v[128:129] op_sel_hi:[1,0]
	v_pk_mul_f32 v[2:3], v[2:3], v[128:129] op_sel_hi:[1,0]
	v_pk_fma_f32 v[146:147], v[226:227], v[20:21], v[146:147]
	v_pk_fma_f32 v[148:149], v[228:229], v[22:23], v[148:149]
	v_pk_fma_f32 v[150:151], v[230:231], v[16:17], v[150:151]
	v_pk_fma_f32 v[152:153], v[232:233], v[18:19], v[152:153]
	v_pk_fma_f32 v[154:155], v[234:235], v[4:5], v[154:155]
	v_pk_fma_f32 v[156:157], v[236:237], v[6:7], v[156:157]
	v_pk_fma_f32 v[158:159], v[238:239], v[0:1], v[158:159]
	v_pk_fma_f32 v[160:161], v[240:241], v[2:3], v[160:161]
	global_store_dwordx4 v242, v[146:149], s[22:23]
	global_store_dwordx4 v242, v[150:153], s[22:23] offset:16
	global_store_dwordx4 v242, v[154:157], s[22:23] offset:512
	global_store_dwordx4 v242, v[158:161], s[22:23] offset:528

	.amdhsa_kernel _Z14fwd_megakernel4Args
		.amdhsa_group_segment_fixed_size 0
		.amdhsa_private_segment_fixed_size 0
		.amdhsa_kernarg_size 496
		.amdhsa_user_sgpr_count 2
		.amdhsa_user_sgpr_dispatch_ptr 0
		.amdhsa_user_sgpr_queue_ptr 0
		.amdhsa_user_sgpr_kernarg_segment_ptr 1
		.amdhsa_user_sgpr_dispatch_id 0
		.amdhsa_user_sgpr_kernarg_preload_length 0
		.amdhsa_user_sgpr_kernarg_preload_offset 0
		.amdhsa_user_sgpr_private_segment_size 0
		.amdhsa_uses_dynamic_stack 0
		.amdhsa_enable_private_segment 0
		.amdhsa_system_sgpr_workgroup_id_x 1
		.amdhsa_system_sgpr_workgroup_id_y 0
		.amdhsa_system_sgpr_workgroup_id_z 0
		.amdhsa_system_sgpr_workgroup_info 0
		.amdhsa_system_vgpr_workitem_id 0
		.amdhsa_next_free_vgpr 256
		.amdhsa_next_free_sgpr 98
		.amdhsa_accum_offset 256
		.amdhsa_reserve_vcc 1
		.amdhsa_float_round_mode_32 0
		.amdhsa_float_round_mode_16_64 0
		.amdhsa_float_denorm_mode_32 3
		.amdhsa_float_denorm_mode_16_64 3
		.amdhsa_dx10_clamp 1
		.amdhsa_ieee_mode 1
		.amdhsa_fp16_overflow 0
		.amdhsa_tg_split 0
		.amdhsa_exception_fp_ieee_invalid_op 0
		.amdhsa_exception_fp_denorm_src 0
		.amdhsa_exception_fp_ieee_div_zero 0
		.amdhsa_exception_fp_ieee_overflow 0
		.amdhsa_exception_fp_ieee_underflow 0
		.amdhsa_exception_fp_ieee_inexact 0
		.amdhsa_exception_int_div_zero 0
	.end_amdhsa_kernel

amdhsa.kernels:
  - .agpr_count:     0
    .args:
      - .offset:         0
        .size:           240
        .value_kind:     by_value
      - .offset:         240
        .size:           4
        .value_kind:     hidden_block_count_x
      - .offset:         244
        .size:           4
        .value_kind:     hidden_block_count_y
      - .offset:         248
        .size:           4
        .value_kind:     hidden_block_count_z
      - .offset:         252
        .size:           2
        .value_kind:     hidden_group_size_x
      - .offset:         254
        .size:           2
        .value_kind:     hidden_group_size_y
      - .offset:         256
        .size:           2
        .value_kind:     hidden_group_size_z
      - .offset:         258
        .size:           2
        .value_kind:     hidden_remainder_x
      - .offset:         260
        .size:           2
        .value_kind:     hidden_remainder_y
      - .offset:         262
        .size:           2
        .value_kind:     hidden_remainder_z
      - .offset:         280
        .size:           8
        .value_kind:     hidden_global_offset_x
      - .offset:         288
        .size:           8
        .value_kind:     hidden_global_offset_y
      - .offset:         296
        .size:           8
        .value_kind:     hidden_global_offset_z
      - .offset:         304
        .size:           2
        .value_kind:     hidden_grid_dims
      - .offset:         360
        .size:           4
        .value_kind:     hidden_dynamic_lds_size
    .group_segment_fixed_size: 0
    .kernarg_segment_align: 8
    .kernarg_segment_size: 496
    .language:       OpenCL C
    .language_version:
      - 2
      - 0
    .max_flat_workgroup_size: 512
    .name:           _Z14fwd_megakernel4Args
    .private_segment_fixed_size: 0
    .sgpr_count:     104
    .sgpr_spill_count: 4
    .symbol:         _Z14fwd_megakernel4Args.kd
    .uniform_work_group_size: 1
    .uses_dynamic_stack: false
    .vgpr_count:     256
    .vgpr_spill_count: 0
    .wavefront_size: 64
